# K-loop heads placed at 64-byte boundary + 4 bytes (odd dword phase)
# speedup vs baseline: 1.0022x; 1.0022x over previous
.LBB0_119:
	s_ashr_i32 s81, s80, 31
	s_lshl_b64 s[52:53], s[80:81], 19
	s_add_u32 s82, s12, s52
	s_addc_u32 s83, s13, s53
	s_and_b64 s[52:53], s[6:7], exec
	s_cselect_b32 s52, s83, s89
	s_cselect_b32 s53, s82, s88
	s_ashr_i32 s79, s78, 31
	s_lshl_b64 s[56:57], s[78:79], 19
	s_add_u32 s84, s14, s56
	s_addc_u32 s85, s15, s57
	s_and_b64 s[56:57], s[6:7], exec
	s_cselect_b32 s56, s85, s91
	s_cselect_b32 s57, s84, s90
	s_add_u32 s88, s88, 0x40080
	s_addc_u32 s89, s89, 0
	s_add_u32 s58, s90, 0x100
	v_mov_b32_e32 v0, 0
	s_addc_u32 s59, s91, 0
	s_mov_b32 s66, -2
	s_waitcnt lgkmcnt(0)
	.p2align 6
	s_nop 0

.LBB0_271:
	s_add_u32 s86, s86, 0xb0080
	s_addc_u32 s87, s87, 0
	s_add_u32 s56, s88, 0x100
	v_mov_b32_e32 v0, 0
	s_addc_u32 s57, s89, 0
	s_mov_b32 s58, -2
	.p2align 6
	s_nop 0

.LBB0_428:
	s_ashr_i32 s95, s94, 31
	s_lshl_b64 s[16:17], s[94:95], 19
	s_add_u32 s96, s12, s16
	s_addc_u32 s97, s13, s17
	s_and_b64 s[16:17], s[8:9], exec
	s_cselect_b32 s15, s97, s89
	s_cselect_b32 s16, s96, s88
	s_ashr_i32 s85, s84, 31
	s_lshl_b64 s[18:19], s[84:85], 19
	s_add_u32 s90, s54, s18
	s_addc_u32 s91, s55, s19
	s_and_b64 s[18:19], s[8:9], exec
	s_cselect_b32 s17, s91, s7
	s_cselect_b32 s18, s90, s6
	s_add_u32 s88, s88, 0x40080
	s_addc_u32 s89, s89, 0
	s_add_u32 s19, s6, 0x100
	v_mov_b32_e32 v0, 0
	s_addc_u32 s20, s7, 0
	s_mov_b32 s21, -2
	s_waitcnt lgkmcnt(0)
	.p2align 6
	s_nop 0

.LBB0_992:
	s_ashr_i32 s53, s52, 31
	s_lshl_b64 s[54:55], s[52:53], 19
	s_add_u32 s76, s42, s54
	s_addc_u32 s77, s43, s55
	s_and_b64 s[54:55], s[6:7], exec
	s_cselect_b32 s53, s77, s83
	s_cselect_b32 s54, s76, s82
	s_ashr_i32 s51, s50, 31
	s_lshl_b64 s[56:57], s[50:51], 19
	s_add_u32 s78, s3, s56
	s_addc_u32 s79, s14, s57
	s_and_b64 s[56:57], s[6:7], exec
	s_cselect_b32 s51, s79, s85
	s_cselect_b32 s55, s78, s84
	s_add_u32 s82, s82, 0x40080
	s_addc_u32 s83, s83, 0
	s_add_u32 s56, s84, 0x100
	v_mov_b32_e32 v0, 0
	s_addc_u32 s57, s85, 0
	s_mov_b32 s58, -2
	.p2align 6
	s_nop 0

.LBB0_1147:
	s_ashr_i32 s49, s48, 31
	s_lshl_b64 s[50:51], s[48:49], 19
	s_add_u32 s50, s12, s50
	s_addc_u32 s51, s13, s51
	s_and_b64 s[52:53], s[4:5], exec
	s_cselect_b32 s49, s51, s79
	s_cselect_b32 s54, s50, s78
	s_ashr_i32 s47, s46, 31
	s_lshl_b64 s[52:53], s[46:47], 19
	s_add_u32 s52, s14, s52
	s_addc_u32 s53, s15, s53
	s_and_b64 s[58:59], s[4:5], exec
	s_cselect_b32 s47, s53, s81
	s_cselect_b32 s55, s52, s80
	s_add_u32 s78, s78, 0x40080
	s_addc_u32 s79, s79, 0
	s_add_u32 s58, s80, 0x100
	v_mov_b32_e32 v0, 0
	s_addc_u32 s59, s81, 0
	s_mov_b32 s66, -2
	s_waitcnt lgkmcnt(0)
	.p2align 6
	s_nop 0

.LBB0_1298:
	s_add_u32 s76, s76, 0xb0080
	s_addc_u32 s77, s77, 0
	s_add_u32 s55, s78, 0x100
	v_mov_b32_e32 v0, 0
	s_addc_u32 s58, s79, 0
	s_mov_b32 s59, -2
	.p2align 6
	s_nop 0

.LBB0_1759:
	s_ashr_i32 s49, s48, 31
	s_lshl_b64 s[50:51], s[48:49], 19
	s_add_u32 s50, s12, s50
	s_addc_u32 s51, s13, s51
	s_and_b64 s[52:53], s[4:5], exec
	s_cselect_b32 s49, s51, s79
	s_cselect_b32 s54, s50, s78
	s_ashr_i32 s47, s46, 31
	s_lshl_b64 s[52:53], s[46:47], 19
	s_add_u32 s52, s14, s52
	s_addc_u32 s53, s15, s53
	s_and_b64 s[66:67], s[4:5], exec
	s_cselect_b32 s47, s53, s81
	s_cselect_b32 s55, s52, s80
	s_add_u32 s78, s78, 0x40080
	s_addc_u32 s79, s79, 0
	s_add_u32 s66, s80, 0x100
	v_mov_b32_e32 v0, 0
	s_addc_u32 s67, s81, 0
	s_mov_b32 s68, -2
	s_waitcnt lgkmcnt(0)
	.p2align 6
	s_nop 0

.LBB0_2036:
	s_ashr_i32 s53, s52, 31
	s_lshl_b64 s[54:55], s[52:53], 19
	s_add_u32 s58, s42, s54
	s_addc_u32 s59, s43, s55
	s_and_b64 s[54:55], s[6:7], exec
	s_cselect_b32 s53, s59, s77
	s_cselect_b32 s54, s58, s76
	s_ashr_i32 s51, s50, 31
	s_lshl_b64 s[56:57], s[50:51], 19
	s_add_u32 s72, s3, s56
	s_addc_u32 s73, s14, s57
	s_and_b64 s[56:57], s[6:7], exec
	s_cselect_b32 s51, s73, s79
	s_cselect_b32 s55, s72, s78
	s_add_u32 s76, s76, 0x40080
	s_addc_u32 s77, s77, 0
	s_add_u32 s56, s78, 0x100
	v_mov_b32_e32 v0, 0
	s_addc_u32 s57, s79, 0
	s_mov_b32 s66, -2
	.p2align 6
	s_nop 0

.LBB0_2191:
	s_ashr_i32 s47, s46, 31
	s_lshl_b64 s[48:49], s[46:47], 19
	s_add_u32 s48, s12, s48
	s_addc_u32 s49, s13, s49
	s_and_b64 s[50:51], s[4:5], exec
	s_cselect_b32 s47, s49, s59
	s_cselect_b32 s53, s48, s58
	s_ashr_i32 s45, s44, 31
	s_lshl_b64 s[50:51], s[44:45], 19
	s_add_u32 s50, s14, s50
	s_addc_u32 s51, s15, s51
	s_and_b64 s[66:67], s[4:5], exec
	s_cselect_b32 s45, s51, s73
	s_cselect_b32 s66, s50, s72
	s_add_u32 s58, s58, 0x40080
	s_addc_u32 s59, s59, 0
	s_add_u32 s67, s72, 0x100
	v_mov_b32_e32 v0, 0
	s_addc_u32 s68, s73, 0
	s_mov_b32 s69, -2
	s_waitcnt lgkmcnt(0)
	.p2align 6
	s_nop 0

.LBB0_2340:
	s_add_u32 s16, s16, 0xb0080
	s_addc_u32 s17, s17, 0
	s_add_u32 s43, s18, 0x100
	v_mov_b32_e32 v0, 0
	s_addc_u32 s44, s19, 0
	s_mov_b32 s45, -2
	.p2align 6
	s_nop 0
